# P0 FFN gate/up transposes: 32 norm-gain loads per item issued together (one wait) instead of 8 serialized groups
# speedup vs baseline: 1.0052x; 1.0023x over previous
; template <class Map>
; DI void p0_transpose(const float* W, int K, int N, bf16_t* WT, const float* gain, const Map map, LAS float* scr, int& base, int gw, int NGW, int lane) {
;     ...
;         const int kb = it / nblk, nb = it % nblk, k0 = 64 * kb, n0 = 32 * nb;
; #pragma unroll
;         for (int i = 0; i < 32; ++i) { const int kk = 2 * i + (lane >> 5); float v = cur[i]; if (gain) v *= gain[k0 + kk]; scr[kk * 33 + (lane & 31)] = v; }
.LBB0_111:
	s_mul_hi_i32 s0, s52, 0x2e8ba2e9
	s_lshr_b32 s1, s0, 31
	s_ashr_i32 s52, s0, 4
	s_add_i32 s52, s52, s1
	v_cndmask_b32_e64 v3, 0, 1, s[86:87]
	v_cmp_ne_u32_e64 s[0:1], 1, v3
	s_andn2_b64 vcc, exec, s[86:87]
	s_lshl_b32 s92, s52, 6
	s_cbranch_vccnz .LBB0_137
	s_ashr_i32 s93, s92, 31
	v_lshl_add_u64 v[236:237], s[92:93], 0, v[100:101]
	v_lshl_add_u64 v[236:237], v[236:237], 2, s[80:81]
	global_load_dword v204, v[236:237], off
	global_load_dword v205, v[236:237], off offset:8
	global_load_dword v206, v[236:237], off offset:16
	global_load_dword v207, v[236:237], off offset:24
	global_load_dword v208, v[236:237], off offset:32
	global_load_dword v209, v[236:237], off offset:40
	global_load_dword v210, v[236:237], off offset:48
	global_load_dword v211, v[236:237], off offset:56
	global_load_dword v212, v[236:237], off offset:64
	global_load_dword v213, v[236:237], off offset:72
	global_load_dword v214, v[236:237], off offset:80
	global_load_dword v215, v[236:237], off offset:88
	global_load_dword v216, v[236:237], off offset:96
	global_load_dword v217, v[236:237], off offset:104
	global_load_dword v218, v[236:237], off offset:112
	global_load_dword v219, v[236:237], off offset:120
	global_load_dword v220, v[236:237], off offset:128
	global_load_dword v221, v[236:237], off offset:136
	global_load_dword v222, v[236:237], off offset:144
	global_load_dword v223, v[236:237], off offset:152
	global_load_dword v224, v[236:237], off offset:160
	global_load_dword v225, v[236:237], off offset:168
	global_load_dword v226, v[236:237], off offset:176
	global_load_dword v227, v[236:237], off offset:184
	global_load_dword v228, v[236:237], off offset:192
	global_load_dword v229, v[236:237], off offset:200
	global_load_dword v230, v[236:237], off offset:208
	global_load_dword v231, v[236:237], off offset:216
	global_load_dword v232, v[236:237], off offset:224
	global_load_dword v233, v[236:237], off offset:232
	global_load_dword v234, v[236:237], off offset:240
	global_load_dword v235, v[236:237], off offset:248
	s_waitcnt vmcnt(0)
	v_or_b32_e32 v36, s92, v100
	v_ashrrev_i32_e32 v37, 31, v36
	s_ashr_i32 s93, s92, 31
	v_lshl_add_u64 v[36:37], v[36:37], 2, s[80:81]
	v_lshl_add_u64 v[38:39], s[92:93], 0, v[100:101]
	v_lshl_add_u64 v[38:39], v[38:39], 2, s[80:81]
	v_mov_b32_e32 v3, v204
	v_mov_b32_e32 v40, v205
	s_nop 0
	v_mov_b32_e32 v36, v206
	v_mov_b32_e32 v37, v207
	v_add_u32_e32 v38, v128, v130
	s_waitcnt vmcnt(3)
	v_mul_f32_e32 v3, v150, v3
	s_waitcnt vmcnt(2)
	v_mul_f32_e32 v39, v151, v40
	ds_write_b32 v145, v3
	ds_write_b32 v38, v39
	s_waitcnt vmcnt(0)
	v_pk_mul_f32 v[36:37], v[104:105], v[36:37]
	s_cbranch_execnz .LBB0_114

; template <class Map>
; DI void p0_transpose(const float* W, int K, int N, bf16_t* WT, const float* gain, const Map map, LAS float* scr, int& base, int gw, int NGW, int lane) {
;     ...
;         const int kb = it / nblk, nb = it % nblk, k0 = 64 * kb, n0 = 32 * nb;
; #pragma unroll
;         for (int i = 0; i < 32; ++i) { const int kk = 2 * i + (lane >> 5); float v = cur[i]; if (gain) v *= gain[k0 + kk]; scr[kk * 33 + (lane & 31)] = v; }
.LBB0_114:
	v_add_u32_e32 v3, v128, v131
	s_and_b64 vcc, exec, s[0:1]
	ds_write2_b32 v3, v36, v37 offset1:66
	s_cbranch_vccnz .LBB0_138
	s_ashr_i32 s93, s92, 31
	v_lshl_add_u64 v[36:37], s[92:93], 0, v[100:101]
	v_lshl_add_u64 v[36:37], v[36:37], 2, s[80:81]
	v_mov_b32_e32 v3, v208
	v_mov_b32_e32 v40, v209
	v_mov_b32_e32 v38, v210
	v_mov_b32_e32 v39, v211
	v_add_u32_e32 v41, v128, v132
	s_waitcnt vmcnt(3)
	v_mul_f32_e32 v3, v152, v3
	s_waitcnt vmcnt(2)
	v_mul_f32_e32 v40, v153, v40
	ds_write2_b32 v41, v3, v40 offset1:66
	s_waitcnt vmcnt(0)
	v_pk_mul_f32 v[36:37], v[106:107], v[38:39]
	s_cbranch_execnz .LBB0_117

; template <class Map>
; DI void p0_transpose(const float* W, int K, int N, bf16_t* WT, const float* gain, const Map map, LAS float* scr, int& base, int gw, int NGW, int lane) {
;     ...
;         const int kb = it / nblk, nb = it % nblk, k0 = 64 * kb, n0 = 32 * nb;
; #pragma unroll
;         for (int i = 0; i < 32; ++i) { const int kk = 2 * i + (lane >> 5); float v = cur[i]; if (gain) v *= gain[k0 + kk]; scr[kk * 33 + (lane & 31)] = v; }
.LBB0_117:
	v_add_u32_e32 v3, v128, v133
	s_and_b64 vcc, exec, s[0:1]
	ds_write2_b32 v3, v36, v37 offset1:66
	s_cbranch_vccnz .LBB0_139
	s_ashr_i32 s93, s92, 31
	v_lshl_add_u64 v[36:37], s[92:93], 0, v[100:101]
	v_lshl_add_u64 v[36:37], v[36:37], 2, s[80:81]
	v_mov_b32_e32 v3, v212
	v_mov_b32_e32 v40, v213
	v_mov_b32_e32 v38, v214
	v_mov_b32_e32 v39, v215
	v_add_u32_e32 v41, v128, v134
	s_waitcnt vmcnt(3)
	v_mul_f32_e32 v3, v154, v3
	s_waitcnt vmcnt(2)
	v_mul_f32_e32 v40, v155, v40
	ds_write2_b32 v41, v3, v40 offset1:66
	s_waitcnt vmcnt(0)
	v_pk_mul_f32 v[36:37], v[108:109], v[38:39]
	s_cbranch_execnz .LBB0_120

; template <class Map>
; DI void p0_transpose(const float* W, int K, int N, bf16_t* WT, const float* gain, const Map map, LAS float* scr, int& base, int gw, int NGW, int lane) {
;     ...
;         const int kb = it / nblk, nb = it % nblk, k0 = 64 * kb, n0 = 32 * nb;
; #pragma unroll
;         for (int i = 0; i < 32; ++i) { const int kk = 2 * i + (lane >> 5); float v = cur[i]; if (gain) v *= gain[k0 + kk]; scr[kk * 33 + (lane & 31)] = v; }
.LBB0_120:
	v_add_u32_e32 v3, v128, v135
	s_and_b64 vcc, exec, s[0:1]
	ds_write2_b32 v3, v36, v37 offset1:66
	s_cbranch_vccnz .LBB0_140
	s_ashr_i32 s93, s92, 31
	v_lshl_add_u64 v[36:37], s[92:93], 0, v[100:101]
	v_lshl_add_u64 v[36:37], v[36:37], 2, s[80:81]
	v_mov_b32_e32 v3, v216
	v_mov_b32_e32 v40, v217
	v_mov_b32_e32 v38, v218
	v_mov_b32_e32 v39, v219
	v_add_u32_e32 v41, v128, v136
	s_waitcnt vmcnt(3)
	v_mul_f32_e32 v3, v156, v3
	s_waitcnt vmcnt(2)
	v_mul_f32_e32 v40, v157, v40
	ds_write2_b32 v41, v3, v40 offset1:66
	s_waitcnt vmcnt(0)
	v_pk_mul_f32 v[36:37], v[110:111], v[38:39]
	s_cbranch_execnz .LBB0_123

; template <class Map>
; DI void p0_transpose(const float* W, int K, int N, bf16_t* WT, const float* gain, const Map map, LAS float* scr, int& base, int gw, int NGW, int lane) {
;     ...
;         const int kb = it / nblk, nb = it % nblk, k0 = 64 * kb, n0 = 32 * nb;
; #pragma unroll
;         for (int i = 0; i < 32; ++i) { const int kk = 2 * i + (lane >> 5); float v = cur[i]; if (gain) v *= gain[k0 + kk]; scr[kk * 33 + (lane & 31)] = v; }
.LBB0_123:
	v_add_u32_e32 v3, v128, v137
	s_and_b64 vcc, exec, s[0:1]
	ds_write2_b32 v3, v36, v37 offset1:66
	s_cbranch_vccnz .LBB0_141
	s_ashr_i32 s93, s92, 31
	v_lshl_add_u64 v[36:37], s[92:93], 0, v[100:101]
	v_lshl_add_u64 v[36:37], v[36:37], 2, s[80:81]
	v_mov_b32_e32 v3, v220
	v_mov_b32_e32 v40, v221
	v_mov_b32_e32 v38, v222
	v_mov_b32_e32 v39, v223
	v_add_u32_e32 v41, v128, v138
	s_waitcnt vmcnt(3)
	v_mul_f32_e32 v3, v158, v3
	s_waitcnt vmcnt(2)
	v_mul_f32_e32 v40, v159, v40
	ds_write2_b32 v41, v3, v40 offset1:66
	s_waitcnt vmcnt(0)
	v_pk_mul_f32 v[36:37], v[112:113], v[38:39]
	s_cbranch_execnz .LBB0_126

; template <class Map>
; DI void p0_transpose(const float* W, int K, int N, bf16_t* WT, const float* gain, const Map map, LAS float* scr, int& base, int gw, int NGW, int lane) {
;     ...
;         const int kb = it / nblk, nb = it % nblk, k0 = 64 * kb, n0 = 32 * nb;
; #pragma unroll
;         for (int i = 0; i < 32; ++i) { const int kk = 2 * i + (lane >> 5); float v = cur[i]; if (gain) v *= gain[k0 + kk]; scr[kk * 33 + (lane & 31)] = v; }
.LBB0_126:
	v_add_u32_e32 v3, v128, v139
	s_and_b64 vcc, exec, s[0:1]
	ds_write2_b32 v3, v36, v37 offset1:66
	s_cbranch_vccnz .LBB0_142
	s_ashr_i32 s93, s92, 31
	v_lshl_add_u64 v[36:37], s[92:93], 0, v[100:101]
	v_lshl_add_u64 v[36:37], v[36:37], 2, s[80:81]
	v_mov_b32_e32 v3, v224
	v_mov_b32_e32 v40, v225
	v_mov_b32_e32 v38, v226
	v_mov_b32_e32 v39, v227
	v_add_u32_e32 v41, v128, v140
	s_waitcnt vmcnt(3)
	v_mul_f32_e32 v3, v160, v3
	s_waitcnt vmcnt(2)
	v_mul_f32_e32 v40, v161, v40
	ds_write2_b32 v41, v3, v40 offset1:66
	s_waitcnt vmcnt(0)
	v_pk_mul_f32 v[36:37], v[114:115], v[38:39]
	s_cbranch_execnz .LBB0_129

; template <class Map>
; DI void p0_transpose(const float* W, int K, int N, bf16_t* WT, const float* gain, const Map map, LAS float* scr, int& base, int gw, int NGW, int lane) {
;     ...
;         const int kb = it / nblk, nb = it % nblk, k0 = 64 * kb, n0 = 32 * nb;
; #pragma unroll
;         for (int i = 0; i < 32; ++i) { const int kk = 2 * i + (lane >> 5); float v = cur[i]; if (gain) v *= gain[k0 + kk]; scr[kk * 33 + (lane & 31)] = v; }
.LBB0_129:
	v_add_u32_e32 v3, v128, v141
	s_and_b64 vcc, exec, s[0:1]
	ds_write2_b32 v3, v36, v37 offset1:66
	s_cbranch_vccnz .LBB0_143
	s_ashr_i32 s93, s92, 31
	v_lshl_add_u64 v[36:37], s[92:93], 0, v[100:101]
	v_lshl_add_u64 v[36:37], v[36:37], 2, s[80:81]
	v_mov_b32_e32 v3, v228
	v_mov_b32_e32 v40, v229
	v_mov_b32_e32 v38, v230
	v_mov_b32_e32 v39, v231
	v_add_u32_e32 v41, v128, v142
	s_waitcnt vmcnt(3)
	v_mul_f32_e32 v3, v162, v3
	s_waitcnt vmcnt(2)
	v_mul_f32_e32 v40, v163, v40
	ds_write2_b32 v41, v3, v40 offset1:66
	s_waitcnt vmcnt(0)
	v_pk_mul_f32 v[36:37], v[116:117], v[38:39]
	s_cbranch_execnz .LBB0_132

; template <class Map>
; DI void p0_transpose(const float* W, int K, int N, bf16_t* WT, const float* gain, const Map map, LAS float* scr, int& base, int gw, int NGW, int lane) {
;     ...
;         const int kb = it / nblk, nb = it % nblk, k0 = 64 * kb, n0 = 32 * nb;
; #pragma unroll
;         for (int i = 0; i < 32; ++i) { const int kk = 2 * i + (lane >> 5); float v = cur[i]; if (gain) v *= gain[k0 + kk]; scr[kk * 33 + (lane & 31)] = v; }
.LBB0_132:
	v_add_u32_e32 v3, v128, v144
	s_and_b64 vcc, exec, s[0:1]
	ds_write2_b32 v3, v36, v37 offset1:66
	s_cbranch_vccnz .LBB0_144
	s_ashr_i32 s93, s92, 31
	v_lshl_add_u64 v[36:37], s[92:93], 0, v[100:101]
	v_lshl_add_u64 v[36:37], v[36:37], 2, s[80:81]
	v_mov_b32_e32 v40, v232
	v_mov_b32_e32 v41, v233
	v_mov_b32_e32 v38, v234
	v_mov_b32_e32 v39, v235
	s_waitcnt vmcnt(3)
	v_mul_f32_e32 v40, v164, v40
	s_waitcnt vmcnt(2)
	v_mul_f32_e32 v41, v165, v41
	ds_write2_b32 v3, v40, v41 offset0:132 offset1:198
	s_waitcnt vmcnt(0)
	v_pk_mul_f32 v[36:37], v[118:119], v[38:39]
	s_cbranch_execnz .LBB0_135

; template <class Map>
; DI void p0_transpose(const float* W, int K, int N, bf16_t* WT, const float* gain, const Map map, LAS float* scr, int& base, int gw, int NGW, int lane) {
;     ...
;         const int kb = it / nblk, nb = it % nblk, k0 = 64 * kb, n0 = 32 * nb;
; #pragma unroll
;         for (int i = 0; i < 32; ++i) { const int kk = 2 * i + (lane >> 5); float v = cur[i]; if (gain) v *= gain[k0 + kk]; scr[kk * 33 + (lane & 31)] = v; }
.LBB0_248:
	s_mul_hi_i32 s0, s52, 0x2e8ba2e9
	s_lshr_b32 s1, s0, 31
	s_ashr_i32 s52, s0, 4
	s_add_i32 s52, s52, s1
	v_cndmask_b32_e64 v3, 0, 1, s[84:85]
	v_cmp_ne_u32_e64 s[0:1], 1, v3
	s_andn2_b64 vcc, exec, s[84:85]
	s_lshl_b32 s90, s52, 6
	s_cbranch_vccnz .LBB0_274
	s_ashr_i32 s91, s90, 31
	v_lshl_add_u64 v[236:237], s[90:91], 0, v[100:101]
	v_lshl_add_u64 v[236:237], v[236:237], 2, s[80:81]
	global_load_dword v204, v[236:237], off
	global_load_dword v205, v[236:237], off offset:8
	global_load_dword v206, v[236:237], off offset:16
	global_load_dword v207, v[236:237], off offset:24
	global_load_dword v208, v[236:237], off offset:32
	global_load_dword v209, v[236:237], off offset:40
	global_load_dword v210, v[236:237], off offset:48
	global_load_dword v211, v[236:237], off offset:56
	global_load_dword v212, v[236:237], off offset:64
	global_load_dword v213, v[236:237], off offset:72
	global_load_dword v214, v[236:237], off offset:80
	global_load_dword v215, v[236:237], off offset:88
	global_load_dword v216, v[236:237], off offset:96
	global_load_dword v217, v[236:237], off offset:104
	global_load_dword v218, v[236:237], off offset:112
	global_load_dword v219, v[236:237], off offset:120
	global_load_dword v220, v[236:237], off offset:128
	global_load_dword v221, v[236:237], off offset:136
	global_load_dword v222, v[236:237], off offset:144
	global_load_dword v223, v[236:237], off offset:152
	global_load_dword v224, v[236:237], off offset:160
	global_load_dword v225, v[236:237], off offset:168
	global_load_dword v226, v[236:237], off offset:176
	global_load_dword v227, v[236:237], off offset:184
	global_load_dword v228, v[236:237], off offset:192
	global_load_dword v229, v[236:237], off offset:200
	global_load_dword v230, v[236:237], off offset:208
	global_load_dword v231, v[236:237], off offset:216
	global_load_dword v232, v[236:237], off offset:224
	global_load_dword v233, v[236:237], off offset:232
	global_load_dword v234, v[236:237], off offset:240
	global_load_dword v235, v[236:237], off offset:248
	s_waitcnt vmcnt(0)
	v_or_b32_e32 v36, s90, v100
	v_ashrrev_i32_e32 v37, 31, v36
	s_ashr_i32 s91, s90, 31
	v_lshl_add_u64 v[36:37], v[36:37], 2, s[80:81]
	v_lshl_add_u64 v[38:39], s[90:91], 0, v[100:101]
	v_lshl_add_u64 v[38:39], v[38:39], 2, s[80:81]
	v_mov_b32_e32 v3, v204
	v_mov_b32_e32 v40, v205
	s_nop 0
	v_mov_b32_e32 v36, v206
	v_mov_b32_e32 v37, v207
	v_add_u32_e32 v38, v128, v130
	s_waitcnt vmcnt(3)
	v_mul_f32_e32 v3, v150, v3
	s_waitcnt vmcnt(2)
	v_mul_f32_e32 v39, v151, v40
	ds_write_b32 v145, v3
	ds_write_b32 v38, v39
	s_waitcnt vmcnt(0)
	v_pk_mul_f32 v[36:37], v[104:105], v[36:37]
	s_cbranch_execnz .LBB0_251

; template <class Map>
; DI void p0_transpose(const float* W, int K, int N, bf16_t* WT, const float* gain, const Map map, LAS float* scr, int& base, int gw, int NGW, int lane) {
;     ...
;         const int kb = it / nblk, nb = it % nblk, k0 = 64 * kb, n0 = 32 * nb;
; #pragma unroll
;         for (int i = 0; i < 32; ++i) { const int kk = 2 * i + (lane >> 5); float v = cur[i]; if (gain) v *= gain[k0 + kk]; scr[kk * 33 + (lane & 31)] = v; }
.LBB0_251:
	v_add_u32_e32 v3, v128, v131
	s_and_b64 vcc, exec, s[0:1]
	ds_write2_b32 v3, v36, v37 offset1:66
	s_cbranch_vccnz .LBB0_275
	s_ashr_i32 s91, s90, 31
	v_lshl_add_u64 v[36:37], s[90:91], 0, v[100:101]
	v_lshl_add_u64 v[36:37], v[36:37], 2, s[80:81]
	v_mov_b32_e32 v3, v208
	v_mov_b32_e32 v40, v209
	v_mov_b32_e32 v38, v210
	v_mov_b32_e32 v39, v211
	v_add_u32_e32 v41, v128, v132
	s_waitcnt vmcnt(3)
	v_mul_f32_e32 v3, v152, v3
	s_waitcnt vmcnt(2)
	v_mul_f32_e32 v40, v153, v40
	ds_write2_b32 v41, v3, v40 offset1:66
	s_waitcnt vmcnt(0)
	v_pk_mul_f32 v[36:37], v[106:107], v[38:39]
	s_cbranch_execnz .LBB0_254

; template <class Map>
; DI void p0_transpose(const float* W, int K, int N, bf16_t* WT, const float* gain, const Map map, LAS float* scr, int& base, int gw, int NGW, int lane) {
;     ...
;         const int kb = it / nblk, nb = it % nblk, k0 = 64 * kb, n0 = 32 * nb;
; #pragma unroll
;         for (int i = 0; i < 32; ++i) { const int kk = 2 * i + (lane >> 5); float v = cur[i]; if (gain) v *= gain[k0 + kk]; scr[kk * 33 + (lane & 31)] = v; }
.LBB0_254:
	v_add_u32_e32 v3, v128, v133
	s_and_b64 vcc, exec, s[0:1]
	ds_write2_b32 v3, v36, v37 offset1:66
	s_cbranch_vccnz .LBB0_276
	s_ashr_i32 s91, s90, 31
	v_lshl_add_u64 v[36:37], s[90:91], 0, v[100:101]
	v_lshl_add_u64 v[36:37], v[36:37], 2, s[80:81]
	v_mov_b32_e32 v3, v212
	v_mov_b32_e32 v40, v213
	v_mov_b32_e32 v38, v214
	v_mov_b32_e32 v39, v215
	v_add_u32_e32 v41, v128, v134
	s_waitcnt vmcnt(3)
	v_mul_f32_e32 v3, v154, v3
	s_waitcnt vmcnt(2)
	v_mul_f32_e32 v40, v155, v40
	ds_write2_b32 v41, v3, v40 offset1:66
	s_waitcnt vmcnt(0)
	v_pk_mul_f32 v[36:37], v[108:109], v[38:39]
	s_cbranch_execnz .LBB0_257

; template <class Map>
; DI void p0_transpose(const float* W, int K, int N, bf16_t* WT, const float* gain, const Map map, LAS float* scr, int& base, int gw, int NGW, int lane) {
;     ...
;         const int kb = it / nblk, nb = it % nblk, k0 = 64 * kb, n0 = 32 * nb;
; #pragma unroll
;         for (int i = 0; i < 32; ++i) { const int kk = 2 * i + (lane >> 5); float v = cur[i]; if (gain) v *= gain[k0 + kk]; scr[kk * 33 + (lane & 31)] = v; }
.LBB0_257:
	v_add_u32_e32 v3, v128, v135
	s_and_b64 vcc, exec, s[0:1]
	ds_write2_b32 v3, v36, v37 offset1:66
	s_cbranch_vccnz .LBB0_277
	s_ashr_i32 s91, s90, 31
	v_lshl_add_u64 v[36:37], s[90:91], 0, v[100:101]
	v_lshl_add_u64 v[36:37], v[36:37], 2, s[80:81]
	v_mov_b32_e32 v3, v216
	v_mov_b32_e32 v40, v217
	v_mov_b32_e32 v38, v218
	v_mov_b32_e32 v39, v219
	v_add_u32_e32 v41, v128, v136
	s_waitcnt vmcnt(3)
	v_mul_f32_e32 v3, v156, v3
	s_waitcnt vmcnt(2)
	v_mul_f32_e32 v40, v157, v40
	ds_write2_b32 v41, v3, v40 offset1:66
	s_waitcnt vmcnt(0)
	v_pk_mul_f32 v[36:37], v[110:111], v[38:39]
	s_cbranch_execnz .LBB0_260

; template <class Map>
; DI void p0_transpose(const float* W, int K, int N, bf16_t* WT, const float* gain, const Map map, LAS float* scr, int& base, int gw, int NGW, int lane) {
;     ...
;         const int kb = it / nblk, nb = it % nblk, k0 = 64 * kb, n0 = 32 * nb;
; #pragma unroll
;         for (int i = 0; i < 32; ++i) { const int kk = 2 * i + (lane >> 5); float v = cur[i]; if (gain) v *= gain[k0 + kk]; scr[kk * 33 + (lane & 31)] = v; }
.LBB0_260:
	v_add_u32_e32 v3, v128, v137
	s_and_b64 vcc, exec, s[0:1]
	ds_write2_b32 v3, v36, v37 offset1:66
	s_cbranch_vccnz .LBB0_278
	s_ashr_i32 s91, s90, 31
	v_lshl_add_u64 v[36:37], s[90:91], 0, v[100:101]
	v_lshl_add_u64 v[36:37], v[36:37], 2, s[80:81]
	v_mov_b32_e32 v3, v220
	v_mov_b32_e32 v40, v221
	v_mov_b32_e32 v38, v222
	v_mov_b32_e32 v39, v223
	v_add_u32_e32 v41, v128, v138
	s_waitcnt vmcnt(3)
	v_mul_f32_e32 v3, v158, v3
	s_waitcnt vmcnt(2)
	v_mul_f32_e32 v40, v159, v40
	ds_write2_b32 v41, v3, v40 offset1:66
	s_waitcnt vmcnt(0)
	v_pk_mul_f32 v[36:37], v[112:113], v[38:39]
	s_cbranch_execnz .LBB0_263

; template <class Map>
; DI void p0_transpose(const float* W, int K, int N, bf16_t* WT, const float* gain, const Map map, LAS float* scr, int& base, int gw, int NGW, int lane) {
;     ...
;         const int kb = it / nblk, nb = it % nblk, k0 = 64 * kb, n0 = 32 * nb;
; #pragma unroll
;         for (int i = 0; i < 32; ++i) { const int kk = 2 * i + (lane >> 5); float v = cur[i]; if (gain) v *= gain[k0 + kk]; scr[kk * 33 + (lane & 31)] = v; }
.LBB0_263:
	v_add_u32_e32 v3, v128, v139
	s_and_b64 vcc, exec, s[0:1]
	ds_write2_b32 v3, v36, v37 offset1:66
	s_cbranch_vccnz .LBB0_279
	s_ashr_i32 s91, s90, 31
	v_lshl_add_u64 v[36:37], s[90:91], 0, v[100:101]
	v_lshl_add_u64 v[36:37], v[36:37], 2, s[80:81]
	v_mov_b32_e32 v3, v224
	v_mov_b32_e32 v40, v225
	v_mov_b32_e32 v38, v226
	v_mov_b32_e32 v39, v227
	v_add_u32_e32 v41, v128, v140
	s_waitcnt vmcnt(3)
	v_mul_f32_e32 v3, v160, v3
	s_waitcnt vmcnt(2)
	v_mul_f32_e32 v40, v161, v40
	ds_write2_b32 v41, v3, v40 offset1:66
	s_waitcnt vmcnt(0)
	v_pk_mul_f32 v[36:37], v[114:115], v[38:39]
	s_cbranch_execnz .LBB0_266

; template <class Map>
; DI void p0_transpose(const float* W, int K, int N, bf16_t* WT, const float* gain, const Map map, LAS float* scr, int& base, int gw, int NGW, int lane) {
;     ...
;         const int kb = it / nblk, nb = it % nblk, k0 = 64 * kb, n0 = 32 * nb;
; #pragma unroll
;         for (int i = 0; i < 32; ++i) { const int kk = 2 * i + (lane >> 5); float v = cur[i]; if (gain) v *= gain[k0 + kk]; scr[kk * 33 + (lane & 31)] = v; }
.LBB0_266:
	v_add_u32_e32 v3, v128, v141
	s_and_b64 vcc, exec, s[0:1]
	ds_write2_b32 v3, v36, v37 offset1:66
	s_cbranch_vccnz .LBB0_280
	s_ashr_i32 s91, s90, 31
	v_lshl_add_u64 v[36:37], s[90:91], 0, v[100:101]
	v_lshl_add_u64 v[36:37], v[36:37], 2, s[80:81]
	v_mov_b32_e32 v3, v228
	v_mov_b32_e32 v40, v229
	v_mov_b32_e32 v38, v230
	v_mov_b32_e32 v39, v231
	v_add_u32_e32 v41, v128, v142
	s_waitcnt vmcnt(3)
	v_mul_f32_e32 v3, v162, v3
	s_waitcnt vmcnt(2)
	v_mul_f32_e32 v40, v163, v40
	ds_write2_b32 v41, v3, v40 offset1:66
	s_waitcnt vmcnt(0)
	v_pk_mul_f32 v[36:37], v[116:117], v[38:39]
	s_cbranch_execnz .LBB0_269

; template <class Map>
; DI void p0_transpose(const float* W, int K, int N, bf16_t* WT, const float* gain, const Map map, LAS float* scr, int& base, int gw, int NGW, int lane) {
;     ...
;         const int kb = it / nblk, nb = it % nblk, k0 = 64 * kb, n0 = 32 * nb;
; #pragma unroll
;         for (int i = 0; i < 32; ++i) { const int kk = 2 * i + (lane >> 5); float v = cur[i]; if (gain) v *= gain[k0 + kk]; scr[kk * 33 + (lane & 31)] = v; }
.LBB0_269:
	v_add_u32_e32 v3, v128, v144
	s_and_b64 vcc, exec, s[0:1]
	ds_write2_b32 v3, v36, v37 offset1:66
	s_cbranch_vccnz .LBB0_281
	s_ashr_i32 s91, s90, 31
	v_lshl_add_u64 v[36:37], s[90:91], 0, v[100:101]
	v_lshl_add_u64 v[36:37], v[36:37], 2, s[80:81]
	v_mov_b32_e32 v40, v232
	v_mov_b32_e32 v41, v233
	v_mov_b32_e32 v38, v234
	v_mov_b32_e32 v39, v235
	s_waitcnt vmcnt(3)
	v_mul_f32_e32 v40, v164, v40
	s_waitcnt vmcnt(2)
	v_mul_f32_e32 v41, v165, v41
	ds_write2_b32 v3, v40, v41 offset0:132 offset1:198
	s_waitcnt vmcnt(0)
	v_pk_mul_f32 v[36:37], v[118:119], v[38:39]
	s_cbranch_execnz .LBB0_272
